# fused epilogue: base-tile load groups 2,3 via LDS-DMA issued with group 1 (4 serialized round trips -> 2)
# baseline (speedup 1.0000x reference)
.LBB0_487:
	s_lshl_b32 s54, s59, 5
	s_sub_i32 s46, s66, 64
	s_and_b64 s[42:43], s[62:63], exec
	s_cselect_b32 s42, s66, s46
	s_ashr_i32 s43, s42, 31
	s_lshl_b64 s[42:43], s[42:43], 20
	s_add_u32 s46, s34, s42
	s_addc_u32 s47, s35, s43
	v_readlane_b32 s34, v255, 9
	s_lshl_b32 s34, s34, 8
	v_readlane_b32 s35, v255, 10
	s_or_b32 s34, s34, s54
	v_lshrrev_b32_e32 v32, 2, v37
	v_and_or_b32 v184, v32, 12, s34
	s_lshl_b64 s[34:35], s[52:53], 2
	s_add_u32 s52, s45, s34
	v_ashrrev_i32_e32 v185, 31, v184
	s_addc_u32 s53, s28, s35
	v_lshlrev_b64 v[186:187], 2, v[184:185]
	v_ashrrev_i32_e32 v35, 31, v34
	v_or_b32_e32 v200, 16, v34
	v_lshl_add_u64 v[138:139], s[52:53], 0, v[186:187]
	v_lshl_add_u64 v[224:225], s[46:47], 0, v[186:187]
	v_lshlrev_b64 v[208:209], 12, v[34:35]
	v_ashrrev_i32_e32 v201, 31, v200
	flat_load_dwordx4 v[134:137], v[138:139]
	flat_load_dwordx4 v[170:173], v[138:139] offset:64
	flat_load_dwordx4 v[162:165], v[138:139] offset:512
	flat_load_dwordx4 v[154:157], v[138:139] offset:576
	v_lshl_add_u64 v[138:139], v[224:225], 0, v[208:209]
	v_lshlrev_b64 v[204:205], 12, v[200:201]
	flat_load_dwordx4 v[188:191], v[138:139]
	flat_load_dwordx4 v[174:177], v[138:139] offset:64
	flat_load_dwordx4 v[166:169], v[138:139] offset:512
	flat_load_dwordx4 v[158:161], v[138:139] offset:576
	v_lshl_add_u64 v[138:139], v[224:225], 0, v[204:205]
	flat_load_dwordx4 v[150:153], v[138:139]
	flat_load_dwordx4 v[146:149], v[138:139] offset:64
	flat_load_dwordx4 v[142:145], v[138:139] offset:512
	s_nop 0
	flat_load_dwordx4 v[138:141], v[138:139] offset:576
	v_readlane_b32 s98, v254, 58
	s_nop 3
	s_lshl_b32 s98, s98, 14
	v_add_u32_e32 v182, 0x20, v34
	v_lshlrev_b32_e32 v182, 12, v182
	v_mov_b32_e32 v183, 0
	v_lshl_add_u64 v[182:183], v[182:183], 0, v[224:225]
	s_mov_b32 m0, s98
	s_nop 0
	global_load_lds_dwordx4 v[182:183], off
	v_lshl_add_u64 v[182:183], v[182:183], 0, 64
	s_add_i32 m0, s98, 0x400
	s_nop 0
	global_load_lds_dwordx4 v[182:183], off
	v_add_co_u32_e32 v182, vcc, 0x1c0, v182
	s_nop 1
	v_addc_co_u32_e32 v183, vcc, 0, v183, vcc
	s_add_i32 m0, s98, 0x800
	s_nop 0
	global_load_lds_dwordx4 v[182:183], off
	v_lshl_add_u64 v[182:183], v[182:183], 0, 64
	s_add_i32 m0, s98, 0xc00
	s_nop 0
	global_load_lds_dwordx4 v[182:183], off
	v_add_u32_e32 v182, 0x30, v34
	v_lshlrev_b32_e32 v182, 12, v182
	v_mov_b32_e32 v183, 0
	v_lshl_add_u64 v[182:183], v[182:183], 0, v[224:225]
	s_add_i32 m0, s98, 0x1000
	s_nop 0
	global_load_lds_dwordx4 v[182:183], off
	v_lshl_add_u64 v[182:183], v[182:183], 0, 64
	s_add_i32 m0, s98, 0x1400
	s_nop 0
	global_load_lds_dwordx4 v[182:183], off
	v_add_co_u32_e32 v182, vcc, 0x1c0, v182
	s_nop 1
	v_addc_co_u32_e32 v183, vcc, 0, v183, vcc
	s_add_i32 m0, s98, 0x1800
	s_nop 0
	global_load_lds_dwordx4 v[182:183], off
	v_lshl_add_u64 v[182:183], v[182:183], 0, 64
	s_add_i32 m0, s98, 0x1c00
	s_nop 0
	global_load_lds_dwordx4 v[182:183], off
	v_add_u32_e32 v182, 0x80, v34
	v_lshlrev_b32_e32 v182, 12, v182
	v_mov_b32_e32 v183, 0
	v_lshl_add_u64 v[182:183], v[182:183], 0, v[224:225]
	s_add_i32 m0, s98, 0x2000
	s_nop 0
	global_load_lds_dwordx4 v[182:183], off
	v_lshl_add_u64 v[182:183], v[182:183], 0, 64
	s_add_i32 m0, s98, 0x2400
	s_nop 0
	global_load_lds_dwordx4 v[182:183], off
	v_add_co_u32_e32 v182, vcc, 0x1c0, v182
	s_nop 1
	v_addc_co_u32_e32 v183, vcc, 0, v183, vcc
	s_add_i32 m0, s98, 0x2800
	s_nop 0
	global_load_lds_dwordx4 v[182:183], off
	v_lshl_add_u64 v[182:183], v[182:183], 0, 64
	s_add_i32 m0, s98, 0x2c00
	s_nop 0
	global_load_lds_dwordx4 v[182:183], off
	v_add_u32_e32 v182, 0x90, v34
	v_lshlrev_b32_e32 v182, 12, v182
	v_mov_b32_e32 v183, 0
	v_lshl_add_u64 v[182:183], v[182:183], 0, v[224:225]
	s_add_i32 m0, s98, 0x3000
	s_nop 0
	global_load_lds_dwordx4 v[182:183], off
	v_lshl_add_u64 v[182:183], v[182:183], 0, 64
	s_add_i32 m0, s98, 0x3400
	s_nop 0
	global_load_lds_dwordx4 v[182:183], off
	v_add_co_u32_e32 v182, vcc, 0x1c0, v182
	s_nop 1
	v_addc_co_u32_e32 v183, vcc, 0, v183, vcc
	s_add_i32 m0, s98, 0x3800
	s_nop 0
	global_load_lds_dwordx4 v[182:183], off
	v_lshl_add_u64 v[182:183], v[182:183], 0, 64
	s_add_i32 m0, s98, 0x3c00
	s_nop 0
	global_load_lds_dwordx4 v[182:183], off
	v_readlane_b32 s52, v254, 36
	s_add_u32 s24, s24, s42
	s_mov_b32 s46, s1
	s_mov_b32 s47, s61
	v_readlane_b32 s53, v254, 37
	s_mov_b32 s52, s1
	s_addc_u32 s25, s25, s43
	s_cmp_eq_u64 s[46:47], s[52:53]
	s_mov_b32 s43, s53
	v_lshl_add_u64 v[210:211], s[24:25], 0, v[186:187]
	s_cselect_b64 s[64:65], -1, 0
	v_writelane_b32 v254, s42, 36
	s_cmp_lg_u64 s[46:47], s[52:53]
	v_lshl_add_u64 v[186:187], v[210:211], 0, v[208:209]
	v_writelane_b32 v254, s43, 37
	s_cselect_b64 s[46:47], -1, 0
	s_and_b64 vcc, exec, s[64:65]
	s_waitcnt vmcnt(16) lgkmcnt(0)
	v_pk_mul_f32 v[220:221], s[60:61], v[136:137] op_sel_hi:[0,1]
	v_pk_mul_f32 v[214:215], s[60:61], v[134:135] op_sel_hi:[0,1]
	v_pk_fma_f32 v[136:137], v[132:133], v[220:221], v[190:191]
	v_pk_fma_f32 v[134:135], v[130:131], v[214:215], v[188:189]
	s_cbranch_vccz .LBB0_489
	flat_store_dwordx4 v[186:187], v[134:137]

.LBB0_500:
	v_or_b32_e32 v202, 32, v34
	v_ashrrev_i32_e32 v203, 31, v202
	v_or_b32_e32 v194, 48, v34
	v_lshlrev_b64 v[206:207], 12, v[202:203]
	v_ashrrev_i32_e32 v195, 31, v194
	v_lshl_add_u64 v[138:139], v[224:225], 0, v[206:207]
	v_lshlrev_b64 v[198:199], 12, v[194:195]
	v_readlane_b32 s98, v254, 58
	s_nop 3
	s_lshl_b32 s98, s98, 14
	v_lshl_add_u32 v182, v229, 4, s98
	s_waitcnt vmcnt(8)
	ds_read_b128 v[102:105], v182
	ds_read_b128 v[162:165], v182 offset:1024
	ds_read_b128 v[158:161], v182 offset:2048
	ds_read_b128 v[154:157], v182 offset:3072
	v_lshl_add_u64 v[138:139], v[224:225], 0, v[198:199]
	ds_read_b128 v[150:153], v182 offset:4096
	ds_read_b128 v[146:149], v182 offset:5120
	ds_read_b128 v[142:145], v182 offset:6144
	s_nop 0
	ds_read_b128 v[138:141], v182 offset:7168
	s_and_b64 vcc, exec, s[42:43]
	v_lshl_add_u64 v[170:171], v[210:211], 0, v[206:207]
	s_waitcnt lgkmcnt(0)
	v_pk_fma_f32 v[104:105], v[100:101], v[220:221], v[104:105]
	v_pk_fma_f32 v[102:103], v[98:99], v[214:215], v[102:103]
	s_cbranch_vccz .LBB0_560
	v_pk_fma_f32 v[100:101], v[96:97], v[218:219], v[164:165]
	s_and_b64 vcc, exec, s[42:43]
	v_pk_fma_f32 v[98:99], v[94:95], v[212:213], v[162:163]
	s_cbranch_vccz .LBB0_561

.LBB0_510:
	v_add_u32_e32 v192, 0x80, v34
	v_ashrrev_i32_e32 v193, 31, v192
	v_add_u32_e32 v186, 0x90, v34
	v_lshlrev_b64 v[196:197], 12, v[192:193]
	v_ashrrev_i32_e32 v187, 31, v186
	v_lshl_add_u64 v[138:139], v[224:225], 0, v[196:197]
	v_lshlrev_b64 v[190:191], 12, v[186:187]
	v_readlane_b32 s98, v254, 58
	s_nop 3
	s_lshl_b32 s98, s98, 14
	v_lshl_add_u32 v182, v229, 4, s98
	s_waitcnt vmcnt(0)
	ds_read_b128 v[70:73], v182 offset:8192
	ds_read_b128 v[162:165], v182 offset:9216
	ds_read_b128 v[158:161], v182 offset:10240
	ds_read_b128 v[154:157], v182 offset:11264
	v_lshl_add_u64 v[138:139], v[224:225], 0, v[190:191]
	ds_read_b128 v[150:153], v182 offset:12288
	ds_read_b128 v[146:149], v182 offset:13312
	ds_read_b128 v[142:145], v182 offset:14336
	s_nop 0
	ds_read_b128 v[138:141], v182 offset:15360
	s_and_b64 vcc, exec, s[42:43]
	v_lshl_add_u64 v[170:171], v[210:211], 0, v[196:197]
	s_waitcnt lgkmcnt(0)
	v_mov_b32_e32 v182, v226
	v_pk_fma_f32 v[72:73], v[68:69], v[220:221], v[72:73]
	v_pk_fma_f32 v[70:71], v[66:67], v[214:215], v[70:71]
	s_cbranch_vccz .LBB0_566
	v_pk_fma_f32 v[68:69], v[64:65], v[218:219], v[164:165]
	s_and_b64 vcc, exec, s[42:43]
	v_pk_fma_f32 v[66:67], v[62:63], v[212:213], v[162:163]
	s_cbranch_vccz .LBB0_567

.LBB0_529:
	v_pk_fma_f32 v[2:3], v[2:3], v[166:167], v[140:141]
	v_pk_fma_f32 v[0:1], v[0:1], v[168:169], v[138:139]
	s_mov_b64 s[42:43], -1
	s_and_b64 vcc, exec, s[46:47]
	s_cbranch_vccz .LBB0_725
	s_barrier
	v_and_b32_e32 v46, 64, v229
	v_xor_b32_e32 v32, 16, v229
	v_add_u32_e32 v47, 64, v46
	v_cmp_lt_i32_e32 vcc, v32, v47
	v_mul_f32_e32 v48, v137, v137
	v_fmac_f32_e32 v48, v136, v136
	v_cndmask_b32_e32 v32, v229, v32, vcc
	v_lshlrev_b32_e32 v46, 2, v32
	v_mul_f32_e32 v32, v135, v135
	v_fmac_f32_e32 v32, v134, v134
	v_add_f32_e32 v32, v32, v48
	v_mul_f32_e32 v48, v131, v131
	v_mul_f32_e32 v49, v133, v133
	v_fmac_f32_e32 v48, v130, v130
	v_fmac_f32_e32 v49, v132, v132
	v_add_f32_e32 v48, v48, v49
	v_add_f32_e32 v32, v32, v48
	v_mul_f32_e32 v48, v127, v127
	v_mul_f32_e32 v49, v129, v129
	v_fmac_f32_e32 v48, v126, v126
	v_fmac_f32_e32 v49, v128, v128
	v_add_f32_e32 v48, v48, v49
	v_add_f32_e32 v32, v32, v48
	v_mul_f32_e32 v48, v123, v123
	v_mul_f32_e32 v49, v125, v125
	v_fmac_f32_e32 v48, v122, v122
	v_fmac_f32_e32 v49, v124, v124
	v_add_f32_e32 v48, v48, v49
	v_add_f32_e32 v32, v32, v48
	ds_bpermute_b32 v48, v46, v32
	v_xor_b32_e32 v49, 32, v229
	v_cmp_lt_i32_e32 vcc, v49, v47
	s_lshl_b32 s28, s59, 2
	s_add_i32 s28, s28, 0
	v_cndmask_b32_e32 v47, v229, v49, vcc
	v_lshlrev_b32_e32 v47, 2, v47
	s_waitcnt lgkmcnt(0)
	v_add_f32_e32 v48, v32, v48
	ds_bpermute_b32 v49, v47, v48
	v_and_b32_e32 v32, 63, v37
	v_cmp_gt_u32_e32 vcc, 16, v32
	s_and_saveexec_b64 s[42:43], vcc
	s_cbranch_execz .LBB0_532
	v_readlane_b32 s38, v255, 34
	s_lshl_b32 s45, s38, 10
	s_add_i32 s45, s28, s45
	s_waitcnt lgkmcnt(0)
	v_add_f32_e32 v48, v48, v49
	v_lshl_add_u32 v49, v178, 4, s45
	ds_write_b32 v49, v48
